# mem_item: staging loads issued up front; key-tile loop hand-rescheduled (batched LDS fragment reads)
# speedup vs baseline: 1.0258x; 1.0258x over previous
.LBB0_372:
	v_and_b32_e32 v3, 64, v229
	v_xor_b32_e32 v2, 1, v229
	v_add_u32_e32 v33, 64, v3
	v_cmp_lt_i32_e32 vcc, v2, v33
	s_ashr_i32 s0, s48, 4
	s_ashr_i32 s1, s0, 31
	v_cndmask_b32_e32 v2, v229, v2, vcc
	v_lshlrev_b32_e32 v39, 2, v2
	v_xor_b32_e32 v2, 2, v229
	v_cmp_lt_i32_e32 vcc, v2, v33
	s_lshl_b64 s[2:3], s[0:1], 19
	s_add_u32 s6, s8, s2
	v_cndmask_b32_e32 v2, v229, v2, vcc
	v_lshlrev_b32_e32 v38, 2, v2
	v_xor_b32_e32 v2, 4, v229
	v_cmp_lt_i32_e32 vcc, v2, v33
	s_addc_u32 s7, s9, s3
	s_lshl_b32 s3, s48, 5
	v_cndmask_b32_e32 v2, v229, v2, vcc
	v_mov_b32_e32 v30, v230
	s_and_b32 s2, s3, 0x180
	v_lshlrev_b32_e32 v37, 2, v2
	v_xor_b32_e32 v2, 8, v229
	s_lshl_b32 s2, s2, 1
	v_cmp_lt_i32_e32 vcc, v2, v33
	v_ashrrev_i32_e32 v18, 4, v30
	s_add_u32 s46, s6, s2
	v_cndmask_b32_e32 v2, v229, v2, vcc
	v_ashrrev_i32_e32 v19, 31, v18
	s_addc_u32 s47, s7, 0
	v_and_b32_e32 v0, 15, v30
	v_lshlrev_b32_e32 v36, 2, v2
	v_lshlrev_b64 v[2:3], 11, v[18:19]
	v_lshlrev_b32_e32 v6, 5, v0
	v_lshlrev_b32_e32 v0, 4, v0
	v_lshl_add_u64 v[2:3], s[46:47], 0, v[2:3]
	v_lshl_add_u64 v[2:3], v[2:3], 0, v[0:1]
	global_load_dword v32, v1, s[38:39]
	global_load_dwordx4 v[10:13], v[2:3], off
	global_load_dwordx4 v[14:17], v[2:3], off offset:1024
	s_nop 0
	global_load_dwordx4 v[2:5], v6, s[66:67] offset:16
	s_nop 0
	global_load_dwordx4 v[6:9], v6, s[66:67]
	v_add_u32_e32 v144, 0x200, v30
	v_ashrrev_i32_e32 v146, 4, v144
	v_ashrrev_i32_e32 v147, 31, v146
	v_lshlrev_b64 v[144:145], 11, v[146:147]
	v_lshl_add_u64 v[144:145], s[46:47], 0, v[144:145]
	v_lshl_add_u64 v[144:145], v[144:145], 0, v[0:1]
	global_load_dwordx4 v[54:57], v[144:145], off
	global_load_dwordx4 v[58:61], v[144:145], off offset:1024
	v_add_u32_e32 v144, 0x400, v30
	v_ashrrev_i32_e32 v146, 4, v144
	v_ashrrev_i32_e32 v147, 31, v146
	v_lshlrev_b64 v[144:145], 11, v[146:147]
	v_lshl_add_u64 v[144:145], s[46:47], 0, v[144:145]
	v_lshl_add_u64 v[144:145], v[144:145], 0, v[0:1]
	global_load_dwordx4 v[62:65], v[144:145], off
	global_load_dwordx4 v[66:69], v[144:145], off offset:1024
	v_add_u32_e32 v144, 0x600, v30
	v_ashrrev_i32_e32 v146, 4, v144
	v_ashrrev_i32_e32 v147, 31, v146
	v_lshlrev_b64 v[144:145], 11, v[146:147]
	v_lshl_add_u64 v[144:145], s[46:47], 0, v[144:145]
	v_lshl_add_u64 v[144:145], v[144:145], 0, v[0:1]
	global_load_dwordx4 v[70:73], v[144:145], off
	global_load_dwordx4 v[74:77], v[144:145], off offset:1024
	v_add_u32_e32 v144, 0x800, v30
	v_ashrrev_i32_e32 v146, 4, v144
	v_ashrrev_i32_e32 v147, 31, v146
	v_lshlrev_b64 v[144:145], 11, v[146:147]
	v_lshl_add_u64 v[144:145], s[46:47], 0, v[144:145]
	v_lshl_add_u64 v[144:145], v[144:145], 0, v[0:1]
	global_load_dwordx4 v[78:81], v[144:145], off
	global_load_dwordx4 v[82:85], v[144:145], off offset:1024
	v_add_u32_e32 v144, 0xa00, v30
	v_ashrrev_i32_e32 v146, 4, v144
	v_ashrrev_i32_e32 v147, 31, v146
	v_lshlrev_b64 v[144:145], 11, v[146:147]
	v_lshl_add_u64 v[144:145], s[46:47], 0, v[144:145]
	v_lshl_add_u64 v[144:145], v[144:145], 0, v[0:1]
	global_load_dwordx4 v[86:89], v[144:145], off
	global_load_dwordx4 v[90:93], v[144:145], off offset:1024
	v_add_u32_e32 v144, 0xc00, v30
	v_ashrrev_i32_e32 v146, 4, v144
	v_ashrrev_i32_e32 v147, 31, v146
	v_lshlrev_b64 v[144:145], 11, v[146:147]
	v_lshl_add_u64 v[144:145], s[46:47], 0, v[144:145]
	v_lshl_add_u64 v[144:145], v[144:145], 0, v[0:1]
	global_load_dwordx4 v[94:97], v[144:145], off
	global_load_dwordx4 v[98:101], v[144:145], off offset:1024
	v_add_u32_e32 v144, 0xe00, v30
	v_ashrrev_i32_e32 v146, 4, v144
	v_ashrrev_i32_e32 v147, 31, v146
	v_lshlrev_b64 v[144:145], 11, v[146:147]
	v_lshl_add_u64 v[144:145], s[46:47], 0, v[144:145]
	v_lshl_add_u64 v[144:145], v[144:145], 0, v[0:1]
	global_load_dwordx4 v[102:105], v[144:145], off
	global_load_dwordx4 v[106:109], v[144:145], off offset:1024
	v_add_u32_e32 v35, 0, v0
	v_add_u32_e32 v34, s4, v0
	s_mov_b32 s6, 0x358637bd
	s_bfe_u32 s13, s3, 0x10008
	s_and_b32 s14, s3, 0x80
	v_bfe_u32 v31, v30, 5, 1
	s_mov_b32 s12, 0
	v_lshl_or_b32 v140, v31, 6, s14
	s_waitcnt vmcnt(17)
	v_and_b32_e32 v21, 0xffff0000, v13
	v_and_b32_e32 v25, 0xffff0000, v11
	v_lshlrev_b32_e32 v20, 16, v13
	v_lshlrev_b32_e32 v22, 16, v12
	v_and_b32_e32 v23, 0xffff0000, v12
	v_lshlrev_b32_e32 v24, 16, v11
	v_and_b32_e32 v27, 0xffff0000, v10
	v_mov_b32_e32 v12, v25
	v_mov_b32_e32 v13, v21
	v_lshlrev_b32_e32 v26, 16, v10
	v_mov_b32_e32 v10, v24
	v_mov_b32_e32 v11, v20
	v_pk_mul_f32 v[12:13], v[12:13], v[12:13]
	v_mov_b32_e32 v28, v27
	v_mov_b32_e32 v29, v23
	v_pk_fma_f32 v[10:11], v[10:11], v[10:11], v[12:13]
	v_mov_b32_e32 v12, v26
	v_mov_b32_e32 v13, v22
	v_pk_mul_f32 v[28:29], v[28:29], v[28:29]
	s_nop 0
	v_pk_fma_f32 v[12:13], v[12:13], v[12:13], v[28:29]
	s_nop 0
	v_pk_add_f32 v[28:29], v[12:13], v[10:11]
	v_mul_lo_u32 v10, v18, s5
	v_add_u32_e32 v50, v35, v10
	v_add_u32_e32 v10, v34, v10
	s_waitcnt vmcnt(16)
	ds_write_b128 v10, v[14:17]
	v_add_u32_e32 v10, 0x200, v30
	v_ashrrev_i32_e32 v40, 4, v10
	v_ashrrev_i32_e32 v41, 31, v40
	v_lshlrev_b64 v[10:11], 11, v[40:41]
	v_lshl_add_u64 v[10:11], s[46:47], 0, v[10:11]
	v_lshl_add_u64 v[14:15], v[10:11], 0, v[0:1]
	s_waitcnt vmcnt(13)
	v_and_b32_e32 v43, 0xffff0000, v57
	v_and_b32_e32 v47, 0xffff0000, v55
	v_lshlrev_b32_e32 v42, 16, v57
	v_lshlrev_b32_e32 v44, 16, v56
	v_and_b32_e32 v45, 0xffff0000, v56
	v_lshlrev_b32_e32 v46, 16, v55
	v_and_b32_e32 v49, 0xffff0000, v54
	v_mov_b32_e32 v12, v47
	v_mov_b32_e32 v13, v43
	v_lshlrev_b32_e32 v48, 16, v54
	v_mov_b32_e32 v10, v46
	v_mov_b32_e32 v11, v42
	v_pk_mul_f32 v[12:13], v[12:13], v[12:13]
	v_mov_b32_e32 v14, v49
	v_mov_b32_e32 v15, v45
	v_pk_fma_f32 v[10:11], v[10:11], v[10:11], v[12:13]
	v_mov_b32_e32 v12, v48
	v_mov_b32_e32 v13, v44
	v_pk_mul_f32 v[14:15], v[14:15], v[14:15]
	s_nop 0
	v_pk_fma_f32 v[12:13], v[12:13], v[12:13], v[14:15]
	v_mov_b64_e32 v[14:15], s[6:7]
	v_pk_add_f32 v[10:11], v[12:13], v[10:11]
	v_mov_b32_e32 v13, v28
	v_mov_b32_e32 v12, v10
	v_mov_b32_e32 v28, v11
	v_pk_add_f32 v[10:11], v[12:13], v[28:29]
	ds_bpermute_b32 v13, v39, v11
	ds_bpermute_b32 v12, v39, v10
	s_lshl_b32 s6, s48, 9
	s_and_b32 s6, s6, 0x600
	s_waitcnt lgkmcnt(0)
	v_pk_add_f32 v[10:11], v[10:11], v[12:13]
	ds_bpermute_b32 v13, v38, v11
	ds_bpermute_b32 v12, v38, v10
	s_waitcnt lgkmcnt(0)
	v_pk_add_f32 v[10:11], v[10:11], v[12:13]
	ds_bpermute_b32 v13, v37, v11
	ds_bpermute_b32 v12, v37, v10
	s_waitcnt lgkmcnt(0)
	v_pk_add_f32 v[10:11], v[10:11], v[12:13]
	ds_bpermute_b32 v13, v36, v11
	ds_bpermute_b32 v12, v36, v10
	s_waitcnt lgkmcnt(0)
	v_pk_add_f32 v[10:11], v[10:11], v[12:13]
	s_nop 0
	v_pk_fma_f32 v[28:29], v[10:11], s[34:35], v[14:15] op_sel_hi:[1,0,0]
	s_nop 0
	v_mul_f32_e32 v10, 0x4b800000, v29
	v_cmp_gt_f32_e64 s[36:37], s95, v29
	v_cmp_gt_f32_e32 vcc, s95, v28
	s_nop 0
	v_cndmask_b32_e64 v10, v29, v10, s[36:37]
	v_rsq_f32_e32 v10, v10
	s_nop 0
	v_mul_f32_e32 v11, 0x45800000, v10
	v_cndmask_b32_e64 v10, v10, v11, s[36:37]
	v_pk_mul_f32 v[12:13], v[10:11], v[26:27] op_sel_hi:[0,1]
	v_pk_mul_f32 v[24:25], v[10:11], v[24:25] op_sel_hi:[0,1]
	v_pk_mul_f32 v[22:23], v[10:11], v[22:23] op_sel_hi:[0,1]
	v_pk_mul_f32 v[10:11], v[10:11], v[20:21] op_sel_hi:[0,1]
	v_pk_mul_f32 v[12:13], v[6:7], v[12:13]
	v_pk_mul_f32 v[24:25], v[8:9], v[24:25]
	v_pk_mul_f32 v[22:23], v[2:3], v[22:23]
	v_pk_mul_f32 v[20:21], v[4:5], v[10:11]
	v_cvt_pk_bf16_f32 v10, v12, v13
	v_cvt_pk_bf16_f32 v11, v24, v25
	v_cvt_pk_bf16_f32 v12, v22, v23
	v_cvt_pk_bf16_f32 v13, v20, v21
	ds_write_b128 v50, v[10:13]
	v_mul_f32_e32 v10, 0x4b800000, v28
	v_cndmask_b32_e32 v10, v28, v10, vcc
	v_rsq_f32_e32 v10, v10
	s_nop 0
	v_mul_f32_e32 v11, 0x45800000, v10
	v_cndmask_b32_e32 v10, v10, v11, vcc
	v_pk_mul_f32 v[20:21], v[10:11], v[46:47] op_sel_hi:[0,1]
	v_pk_mul_f32 v[12:13], v[10:11], v[48:49] op_sel_hi:[0,1]
	v_pk_mul_f32 v[20:21], v[8:9], v[20:21]
	v_pk_mul_f32 v[22:23], v[10:11], v[44:45] op_sel_hi:[0,1]
	v_pk_mul_f32 v[10:11], v[10:11], v[42:43] op_sel_hi:[0,1]
	v_pk_mul_f32 v[12:13], v[6:7], v[12:13]
	v_pk_mul_f32 v[22:23], v[2:3], v[22:23]
	v_pk_mul_f32 v[24:25], v[4:5], v[10:11]
	v_cvt_pk_bf16_f32 v11, v20, v21
	v_mul_lo_u32 v20, v40, s5
	v_cvt_pk_bf16_f32 v10, v12, v13
	v_cvt_pk_bf16_f32 v12, v22, v23
	v_cvt_pk_bf16_f32 v13, v24, v25
	v_add_u32_e32 v21, v35, v20
	ds_write_b128 v21, v[10:13]
	v_add_u32_e32 v10, v34, v20
	s_waitcnt vmcnt(12)
	ds_write_b128 v10, v[58:61]
	v_add_u32_e32 v10, 0x400, v30
	v_ashrrev_i32_e32 v26, 4, v10
	v_ashrrev_i32_e32 v27, 31, v26
	v_lshlrev_b64 v[10:11], 11, v[26:27]
	v_lshl_add_u64 v[10:11], s[46:47], 0, v[10:11]
	v_lshl_add_u64 v[16:17], v[10:11], 0, v[0:1]
	s_waitcnt vmcnt(11)
	v_and_b32_e32 v17, 0xffff0000, v65
	v_and_b32_e32 v21, 0xffff0000, v63
	v_lshlrev_b32_e32 v16, 16, v65
	v_lshlrev_b32_e32 v18, 16, v64
	v_and_b32_e32 v19, 0xffff0000, v64
	v_lshlrev_b32_e32 v20, 16, v63
	v_and_b32_e32 v23, 0xffff0000, v62
	v_mov_b32_e32 v12, v21
	v_mov_b32_e32 v13, v17
	v_lshlrev_b32_e32 v22, 16, v62
	v_mov_b32_e32 v10, v20
	v_mov_b32_e32 v11, v16
	v_pk_mul_f32 v[12:13], v[12:13], v[12:13]
	v_mov_b32_e32 v24, v23
	v_mov_b32_e32 v25, v19
	v_pk_fma_f32 v[10:11], v[10:11], v[10:11], v[12:13]
	v_mov_b32_e32 v12, v22
	v_mov_b32_e32 v13, v18
	v_pk_mul_f32 v[24:25], v[24:25], v[24:25]
	s_nop 0
	v_pk_fma_f32 v[12:13], v[12:13], v[12:13], v[24:25]
	s_nop 0
	v_pk_add_f32 v[24:25], v[12:13], v[10:11]
	v_mul_lo_u32 v10, v26, s5
	v_add_u32_e32 v28, v35, v10
	v_add_u32_e32 v10, v34, v10
	s_waitcnt vmcnt(10)
	ds_write_b128 v10, v[66:69]
	v_add_u32_e32 v10, 0x600, v30
	v_ashrrev_i32_e32 v26, 4, v10
	v_ashrrev_i32_e32 v27, 31, v26
	v_lshlrev_b64 v[10:11], 11, v[26:27]
	v_lshl_add_u64 v[10:11], s[46:47], 0, v[10:11]
	v_lshl_add_u64 v[40:41], v[10:11], 0, v[0:1]
	s_nop 0
	s_waitcnt vmcnt(9)
	v_and_b32_e32 v45, 0xffff0000, v73
	v_and_b32_e32 v49, 0xffff0000, v71
	v_lshlrev_b32_e32 v44, 16, v73
	v_lshlrev_b32_e32 v46, 16, v72
	v_and_b32_e32 v47, 0xffff0000, v72
	v_lshlrev_b32_e32 v48, 16, v71
	v_and_b32_e32 v51, 0xffff0000, v70
	v_mov_b32_e32 v12, v49
	v_mov_b32_e32 v13, v45
	v_lshlrev_b32_e32 v50, 16, v70
	v_mov_b32_e32 v10, v48
	v_mov_b32_e32 v11, v44
	v_pk_mul_f32 v[12:13], v[12:13], v[12:13]
	v_mov_b32_e32 v52, v51
	v_mov_b32_e32 v53, v47
	v_pk_fma_f32 v[10:11], v[10:11], v[10:11], v[12:13]
	v_mov_b32_e32 v12, v50
	v_mov_b32_e32 v13, v46
	v_pk_mul_f32 v[52:53], v[52:53], v[52:53]
	s_nop 0
	v_pk_fma_f32 v[12:13], v[12:13], v[12:13], v[52:53]
	s_nop 0
	v_pk_add_f32 v[10:11], v[12:13], v[10:11]
	v_mov_b32_e32 v13, v24
	v_mov_b32_e32 v12, v10
	v_mov_b32_e32 v24, v11
	v_pk_add_f32 v[10:11], v[12:13], v[24:25]
	ds_bpermute_b32 v13, v39, v11
	ds_bpermute_b32 v12, v39, v10
	s_waitcnt lgkmcnt(0)
	v_pk_add_f32 v[10:11], v[10:11], v[12:13]
	ds_bpermute_b32 v13, v38, v11
	ds_bpermute_b32 v12, v38, v10
	s_waitcnt lgkmcnt(0)
	v_pk_add_f32 v[10:11], v[10:11], v[12:13]
	ds_bpermute_b32 v13, v37, v11
	ds_bpermute_b32 v12, v37, v10
	s_waitcnt lgkmcnt(0)
	v_pk_add_f32 v[10:11], v[10:11], v[12:13]
	ds_bpermute_b32 v13, v36, v11
	ds_bpermute_b32 v12, v36, v10
	s_waitcnt lgkmcnt(0)
	v_pk_add_f32 v[10:11], v[10:11], v[12:13]
	s_nop 0
	v_pk_fma_f32 v[24:25], v[10:11], s[34:35], v[14:15] op_sel_hi:[1,0,0]
	s_nop 0
	v_mul_f32_e32 v10, 0x4b800000, v25
	v_cmp_gt_f32_e64 s[36:37], s95, v25
	v_cmp_gt_f32_e32 vcc, s95, v24
	s_nop 0
	v_cndmask_b32_e64 v10, v25, v10, s[36:37]
	v_rsq_f32_e32 v10, v10
	s_nop 0
	v_mul_f32_e32 v11, 0x45800000, v10
	v_cndmask_b32_e64 v10, v10, v11, s[36:37]
	v_pk_mul_f32 v[12:13], v[10:11], v[22:23] op_sel_hi:[0,1]
	v_pk_mul_f32 v[20:21], v[10:11], v[20:21] op_sel_hi:[0,1]
	v_pk_mul_f32 v[18:19], v[10:11], v[18:19] op_sel_hi:[0,1]
	v_pk_mul_f32 v[10:11], v[10:11], v[16:17] op_sel_hi:[0,1]
	v_pk_mul_f32 v[12:13], v[6:7], v[12:13]
	v_pk_mul_f32 v[20:21], v[8:9], v[20:21]
	v_pk_mul_f32 v[18:19], v[2:3], v[18:19]
	v_pk_mul_f32 v[16:17], v[4:5], v[10:11]
	v_cvt_pk_bf16_f32 v10, v12, v13
	v_cvt_pk_bf16_f32 v11, v20, v21
	v_cvt_pk_bf16_f32 v12, v18, v19
	v_cvt_pk_bf16_f32 v13, v16, v17
	ds_write_b128 v28, v[10:13]
	v_mul_f32_e32 v10, 0x4b800000, v24
	v_cndmask_b32_e32 v10, v24, v10, vcc
	v_rsq_f32_e32 v10, v10
	s_nop 0
	v_mul_f32_e32 v11, 0x45800000, v10
	v_cndmask_b32_e32 v10, v10, v11, vcc
	v_pk_mul_f32 v[16:17], v[10:11], v[48:49] op_sel_hi:[0,1]
	v_pk_mul_f32 v[12:13], v[10:11], v[50:51] op_sel_hi:[0,1]
	v_pk_mul_f32 v[16:17], v[8:9], v[16:17]
	v_pk_mul_f32 v[18:19], v[10:11], v[46:47] op_sel_hi:[0,1]
	v_pk_mul_f32 v[10:11], v[10:11], v[44:45] op_sel_hi:[0,1]
	v_pk_mul_f32 v[12:13], v[6:7], v[12:13]
	v_pk_mul_f32 v[18:19], v[2:3], v[18:19]
	v_pk_mul_f32 v[20:21], v[4:5], v[10:11]
	v_cvt_pk_bf16_f32 v11, v16, v17
	v_mul_lo_u32 v16, v26, s5
	v_cvt_pk_bf16_f32 v10, v12, v13
	v_cvt_pk_bf16_f32 v12, v18, v19
	v_cvt_pk_bf16_f32 v13, v20, v21
	v_add_u32_e32 v17, v35, v16
	ds_write_b128 v17, v[10:13]
	v_add_u32_e32 v10, v34, v16
	s_waitcnt vmcnt(8)
	ds_write_b128 v10, v[74:77]
	v_add_u32_e32 v10, 0x800, v30
	v_ashrrev_i32_e32 v26, 4, v10
	v_ashrrev_i32_e32 v27, 31, v26
	v_lshlrev_b64 v[10:11], 11, v[26:27]
	v_lshl_add_u64 v[10:11], s[46:47], 0, v[10:11]
	v_lshl_add_u64 v[16:17], v[10:11], 0, v[0:1]
	s_waitcnt vmcnt(7)
	v_and_b32_e32 v17, 0xffff0000, v81
	v_and_b32_e32 v21, 0xffff0000, v79
	v_lshlrev_b32_e32 v16, 16, v81
	v_lshlrev_b32_e32 v18, 16, v80
	v_and_b32_e32 v19, 0xffff0000, v80
	v_lshlrev_b32_e32 v20, 16, v79
	v_and_b32_e32 v23, 0xffff0000, v78
	v_mov_b32_e32 v12, v21
	v_mov_b32_e32 v13, v17
	v_lshlrev_b32_e32 v22, 16, v78
	v_mov_b32_e32 v10, v20
	v_mov_b32_e32 v11, v16
	v_pk_mul_f32 v[12:13], v[12:13], v[12:13]
	v_mov_b32_e32 v24, v23
	v_mov_b32_e32 v25, v19
	v_pk_fma_f32 v[10:11], v[10:11], v[10:11], v[12:13]
	v_mov_b32_e32 v12, v22
	v_mov_b32_e32 v13, v18
	v_pk_mul_f32 v[24:25], v[24:25], v[24:25]
	s_nop 0
	v_pk_fma_f32 v[12:13], v[12:13], v[12:13], v[24:25]
	s_nop 0
	v_pk_add_f32 v[24:25], v[12:13], v[10:11]
	v_mul_lo_u32 v10, v26, s5
	v_add_u32_e32 v28, v35, v10
	v_add_u32_e32 v10, v34, v10
	s_waitcnt vmcnt(6)
	ds_write_b128 v10, v[82:85]
	v_add_u32_e32 v10, 0xa00, v30
	v_ashrrev_i32_e32 v26, 4, v10
	v_ashrrev_i32_e32 v27, 31, v26
	v_lshlrev_b64 v[10:11], 11, v[26:27]
	v_lshl_add_u64 v[10:11], s[46:47], 0, v[10:11]
	v_lshl_add_u64 v[40:41], v[10:11], 0, v[0:1]
	s_nop 0
	s_waitcnt vmcnt(5)
	v_and_b32_e32 v45, 0xffff0000, v89
	v_and_b32_e32 v49, 0xffff0000, v87
	v_lshlrev_b32_e32 v44, 16, v89
	v_lshlrev_b32_e32 v46, 16, v88
	v_and_b32_e32 v47, 0xffff0000, v88
	v_lshlrev_b32_e32 v48, 16, v87
	v_and_b32_e32 v51, 0xffff0000, v86
	v_mov_b32_e32 v12, v49
	v_mov_b32_e32 v13, v45
	v_lshlrev_b32_e32 v50, 16, v86
	v_mov_b32_e32 v10, v48
	v_mov_b32_e32 v11, v44
	v_pk_mul_f32 v[12:13], v[12:13], v[12:13]
	v_mov_b32_e32 v52, v51
	v_mov_b32_e32 v53, v47
	v_pk_fma_f32 v[10:11], v[10:11], v[10:11], v[12:13]
	v_mov_b32_e32 v12, v50
	v_mov_b32_e32 v13, v46
	v_pk_mul_f32 v[52:53], v[52:53], v[52:53]
	s_nop 0
	v_pk_fma_f32 v[12:13], v[12:13], v[12:13], v[52:53]
	s_nop 0
	v_pk_add_f32 v[10:11], v[12:13], v[10:11]
	v_mov_b32_e32 v13, v24
	v_mov_b32_e32 v12, v10
	v_mov_b32_e32 v24, v11
	v_pk_add_f32 v[10:11], v[12:13], v[24:25]
	ds_bpermute_b32 v13, v39, v11
	ds_bpermute_b32 v12, v39, v10
	s_waitcnt lgkmcnt(0)
	v_pk_add_f32 v[10:11], v[10:11], v[12:13]
	ds_bpermute_b32 v13, v38, v11
	ds_bpermute_b32 v12, v38, v10
	s_waitcnt lgkmcnt(0)
	v_pk_add_f32 v[10:11], v[10:11], v[12:13]
	ds_bpermute_b32 v13, v37, v11
	ds_bpermute_b32 v12, v37, v10
	s_waitcnt lgkmcnt(0)
	v_pk_add_f32 v[10:11], v[10:11], v[12:13]
	ds_bpermute_b32 v13, v36, v11
	ds_bpermute_b32 v12, v36, v10
	s_waitcnt lgkmcnt(0)
	v_pk_add_f32 v[10:11], v[10:11], v[12:13]
	s_nop 0
	v_pk_fma_f32 v[24:25], v[10:11], s[34:35], v[14:15] op_sel_hi:[1,0,0]
	s_nop 0
	v_mul_f32_e32 v10, 0x4b800000, v25
	v_cmp_gt_f32_e64 s[36:37], s95, v25
	v_cmp_gt_f32_e32 vcc, s95, v24
	s_nop 0
	v_cndmask_b32_e64 v10, v25, v10, s[36:37]
	v_rsq_f32_e32 v10, v10
	s_nop 0
	v_mul_f32_e32 v11, 0x45800000, v10
	v_cndmask_b32_e64 v10, v10, v11, s[36:37]
	v_pk_mul_f32 v[12:13], v[10:11], v[22:23] op_sel_hi:[0,1]
	v_pk_mul_f32 v[20:21], v[10:11], v[20:21] op_sel_hi:[0,1]
	v_pk_mul_f32 v[18:19], v[10:11], v[18:19] op_sel_hi:[0,1]
	v_pk_mul_f32 v[10:11], v[10:11], v[16:17] op_sel_hi:[0,1]
	v_pk_mul_f32 v[12:13], v[6:7], v[12:13]
	v_pk_mul_f32 v[20:21], v[8:9], v[20:21]
	v_pk_mul_f32 v[18:19], v[2:3], v[18:19]
	v_pk_mul_f32 v[16:17], v[4:5], v[10:11]
	v_cvt_pk_bf16_f32 v10, v12, v13
	v_cvt_pk_bf16_f32 v11, v20, v21
	v_cvt_pk_bf16_f32 v12, v18, v19
	v_cvt_pk_bf16_f32 v13, v16, v17
	ds_write_b128 v28, v[10:13]
	v_mul_f32_e32 v10, 0x4b800000, v24
	v_cndmask_b32_e32 v10, v24, v10, vcc
	v_rsq_f32_e32 v10, v10
	s_nop 0
	v_mul_f32_e32 v11, 0x45800000, v10
	v_cndmask_b32_e32 v10, v10, v11, vcc
	v_pk_mul_f32 v[16:17], v[10:11], v[48:49] op_sel_hi:[0,1]
	v_pk_mul_f32 v[12:13], v[10:11], v[50:51] op_sel_hi:[0,1]
	v_pk_mul_f32 v[16:17], v[8:9], v[16:17]
	v_pk_mul_f32 v[18:19], v[10:11], v[46:47] op_sel_hi:[0,1]
	v_pk_mul_f32 v[10:11], v[10:11], v[44:45] op_sel_hi:[0,1]
	v_pk_mul_f32 v[12:13], v[6:7], v[12:13]
	v_pk_mul_f32 v[18:19], v[2:3], v[18:19]
	v_pk_mul_f32 v[20:21], v[4:5], v[10:11]
	v_cvt_pk_bf16_f32 v11, v16, v17
	v_mul_lo_u32 v16, v26, s5
	v_cvt_pk_bf16_f32 v10, v12, v13
	v_cvt_pk_bf16_f32 v12, v18, v19
	v_cvt_pk_bf16_f32 v13, v20, v21
	v_add_u32_e32 v17, v35, v16
	ds_write_b128 v17, v[10:13]
	v_add_u32_e32 v10, v34, v16
	s_waitcnt vmcnt(4)
	ds_write_b128 v10, v[90:93]
	v_add_u32_e32 v10, 0xc00, v30
	v_ashrrev_i32_e32 v40, 4, v10
	v_ashrrev_i32_e32 v41, 31, v40
	v_lshlrev_b64 v[10:11], 11, v[40:41]
	v_lshl_add_u64 v[10:11], s[46:47], 0, v[10:11]
	v_lshl_add_u64 v[16:17], v[10:11], 0, v[0:1]
	s_waitcnt vmcnt(3)
	v_and_b32_e32 v17, 0xffff0000, v97
	v_and_b32_e32 v21, 0xffff0000, v95
	v_lshlrev_b32_e32 v16, 16, v97
	v_lshlrev_b32_e32 v18, 16, v96
	v_and_b32_e32 v19, 0xffff0000, v96
	v_lshlrev_b32_e32 v20, 16, v95
	v_and_b32_e32 v23, 0xffff0000, v94
	v_mov_b32_e32 v12, v21
	v_mov_b32_e32 v13, v17
	v_lshlrev_b32_e32 v22, 16, v94
	v_mov_b32_e32 v10, v20
	v_mov_b32_e32 v11, v16
	v_pk_mul_f32 v[12:13], v[12:13], v[12:13]
	v_mov_b32_e32 v24, v23
	v_mov_b32_e32 v25, v19
	v_pk_fma_f32 v[10:11], v[10:11], v[10:11], v[12:13]
	v_mov_b32_e32 v12, v22
	v_mov_b32_e32 v13, v18
	v_pk_mul_f32 v[24:25], v[24:25], v[24:25]
	s_nop 0
	v_pk_fma_f32 v[12:13], v[12:13], v[12:13], v[24:25]
	s_nop 0
	v_pk_add_f32 v[24:25], v[12:13], v[10:11]
	v_mul_lo_u32 v10, v40, s5
	v_add_u32_e32 v40, v35, v10
	v_add_u32_e32 v10, v34, v10
	s_waitcnt vmcnt(2)
	ds_write_b128 v10, v[98:101]
	v_add_u32_e32 v10, 0xe00, v30
	v_ashrrev_i32_e32 v26, 4, v10
	v_ashrrev_i32_e32 v27, 31, v26
	v_lshlrev_b64 v[10:11], 11, v[26:27]
	v_lshl_add_u64 v[10:11], s[46:47], 0, v[10:11]
	v_lshl_add_u64 v[28:29], v[10:11], 0, v[0:1]
	s_waitcnt vmcnt(1)
	v_and_b32_e32 v29, 0xffff0000, v105
	v_and_b32_e32 v49, 0xffff0000, v103
	v_lshlrev_b32_e32 v28, 16, v105
	v_lshlrev_b32_e32 v46, 16, v104
	v_and_b32_e32 v47, 0xffff0000, v104
	v_lshlrev_b32_e32 v48, 16, v103
	v_and_b32_e32 v51, 0xffff0000, v102
	v_mov_b32_e32 v12, v49
	v_mov_b32_e32 v13, v29
	v_lshlrev_b32_e32 v50, 16, v102
	v_mov_b32_e32 v10, v48
	v_mov_b32_e32 v11, v28
	v_pk_mul_f32 v[12:13], v[12:13], v[12:13]
	v_mov_b32_e32 v52, v51
	v_mov_b32_e32 v53, v47
	v_pk_fma_f32 v[10:11], v[10:11], v[10:11], v[12:13]
	v_mov_b32_e32 v12, v50
	v_mov_b32_e32 v13, v46
	v_pk_mul_f32 v[52:53], v[52:53], v[52:53]
	s_nop 0
	v_pk_fma_f32 v[12:13], v[12:13], v[12:13], v[52:53]
	s_nop 0
	v_pk_add_f32 v[10:11], v[12:13], v[10:11]
	v_mov_b32_e32 v13, v24
	v_mov_b32_e32 v12, v10
	v_mov_b32_e32 v24, v11
	v_pk_add_f32 v[10:11], v[12:13], v[24:25]
	ds_bpermute_b32 v13, v39, v11
	ds_bpermute_b32 v12, v39, v10
	s_waitcnt lgkmcnt(0)
	v_pk_add_f32 v[10:11], v[10:11], v[12:13]
	ds_bpermute_b32 v13, v38, v11
	ds_bpermute_b32 v12, v38, v10
	s_waitcnt lgkmcnt(0)
	v_pk_add_f32 v[10:11], v[10:11], v[12:13]
	ds_bpermute_b32 v13, v37, v11
	ds_bpermute_b32 v12, v37, v10
	s_waitcnt lgkmcnt(0)
	v_pk_add_f32 v[10:11], v[10:11], v[12:13]
	ds_bpermute_b32 v13, v36, v11
	ds_bpermute_b32 v12, v36, v10
	s_waitcnt lgkmcnt(0)
	v_pk_add_f32 v[10:11], v[10:11], v[12:13]
	s_nop 0
	v_pk_fma_f32 v[14:15], v[10:11], s[34:35], v[14:15] op_sel_hi:[1,0,0]
	s_nop 0
	v_mul_f32_e32 v0, 0x4b800000, v15
	v_cmp_gt_f32_e64 s[36:37], s95, v15
	v_cmp_gt_f32_e32 vcc, s95, v14
	s_nop 0
	v_cndmask_b32_e64 v0, v15, v0, s[36:37]
	v_rsq_f32_e32 v0, v0
	s_nop 0
	v_mul_f32_e32 v10, 0x45800000, v0
	v_cndmask_b32_e64 v0, v0, v10, s[36:37]
	v_pk_mul_f32 v[10:11], v[0:1], v[22:23] op_sel_hi:[0,1]
	v_pk_mul_f32 v[12:13], v[0:1], v[20:21] op_sel_hi:[0,1]
	v_pk_mul_f32 v[18:19], v[0:1], v[18:19] op_sel_hi:[0,1]
	v_pk_mul_f32 v[16:17], v[0:1], v[16:17] op_sel_hi:[0,1]
	v_mul_f32_e32 v0, 0x4b800000, v14
	v_cndmask_b32_e32 v0, v14, v0, vcc
	v_rsq_f32_e32 v0, v0
	v_pk_mul_f32 v[10:11], v[6:7], v[10:11]
	v_pk_mul_f32 v[12:13], v[8:9], v[12:13]
	v_pk_mul_f32 v[18:19], v[2:3], v[18:19]
	v_pk_mul_f32 v[16:17], v[4:5], v[16:17]
	v_cvt_pk_bf16_f32 v10, v10, v11
	v_cvt_pk_bf16_f32 v11, v12, v13
	v_cvt_pk_bf16_f32 v12, v18, v19
	v_cvt_pk_bf16_f32 v13, v16, v17
	ds_write_b128 v40, v[10:13]
	v_mul_f32_e32 v10, 0x45800000, v0
	v_cndmask_b32_e32 v0, v0, v10, vcc
	v_pk_mul_f32 v[10:11], v[0:1], v[50:51] op_sel_hi:[0,1]
	v_pk_mul_f32 v[6:7], v[6:7], v[10:11]
	v_pk_mul_f32 v[10:11], v[0:1], v[48:49] op_sel_hi:[0,1]
	v_pk_mul_f32 v[8:9], v[8:9], v[10:11]
	v_pk_mul_f32 v[10:11], v[0:1], v[46:47] op_sel_hi:[0,1]
	v_pk_mul_f32 v[10:11], v[2:3], v[10:11]
	v_pk_mul_f32 v[2:3], v[0:1], v[28:29] op_sel_hi:[0,1]
	v_mul_lo_u32 v0, v26, s5
	v_pk_mul_f32 v[12:13], v[4:5], v[2:3]
	v_cvt_pk_bf16_f32 v2, v6, v7
	v_add_u32_e32 v6, v35, v0
	v_add_u32_e32 v0, v34, v0
	s_waitcnt vmcnt(0)
	ds_write_b128 v0, v[106:109]
	v_and_b32_e32 v0, 0xffffffc0, v30
	v_add_u32_e32 v22, s6, v0
	v_xor_b32_e32 v0, 32, v229
	s_lshl_b64 s[6:7], s[0:1], 21
	v_cmp_lt_i32_e32 vcc, v0, v33
	s_add_u32 s1, s10, s6
	s_addc_u32 s3, s11, s7
	v_cndmask_b32_e32 v0, v229, v0, vcc
	v_lshlrev_b32_e32 v138, 2, v0
	v_lshlrev_b32_e32 v0, 8, v31
	s_add_u32 s2, s1, s2
	v_lshl_add_u64 v[130:131], s[64:65], 0, v[0:1]
	s_addc_u32 s3, s3, 0
	v_lshlrev_b32_e32 v0, 3, v31
	v_lshl_add_u64 v[132:133], s[2:3], 0, v[0:1]
	v_lshl_add_u32 v0, s0, 11, v22
	v_lshrrev_b32_e32 v0, 8, v0
	v_mul_i32_i24_e32 v0, 38, v0
	v_or_b32_e32 v0, s13, v0
	v_add_u32_e32 v18, 24, v0
	v_ashrrev_i32_e32 v19, 31, v18
	v_and_b32_e32 v20, 31, v30
	v_lshlrev_b64 v[18:19], 17, v[18:19]
	v_bfe_u32 v21, v30, 2, 2
	v_lshlrev_b32_e32 v23, 7, v31
	v_lshl_add_u64 v[134:135], s[40:41], 0, v[18:19]
	v_mul_u32_u24_e32 v0, 0x110, v20
	v_lshlrev_b32_e32 v19, 1, v30
	v_add3_u32 v141, v0, v23, 0
	v_mul_u32_u24_e32 v0, 0x440, v31
	v_mul_u32_u24_e32 v18, 0x110, v21
	v_and_b32_e32 v19, 32, v19
	v_cvt_pk_bf16_f32 v3, v8, v9
	v_cvt_pk_bf16_f32 v4, v10, v11
	v_cvt_pk_bf16_f32 v5, v12, v13
	v_add3_u32 v0, v0, v18, v19
	v_and_b32_e32 v18, 3, v30
	ds_write_b128 v6, v[2:5]
	v_xor_b32_e32 v2, 0x80000000, v32
	v_lshlrev_b32_e32 v18, 3, v18
	v_mov_b32_e32 v3, v2
	v_mov_b32_e32 v4, v2
	v_mov_b32_e32 v5, v2
	v_mov_b32_e32 v6, v2
	v_mov_b32_e32 v7, v2
	v_mov_b32_e32 v8, v2
	v_mov_b32_e32 v9, v2
	v_mov_b32_e32 v10, v2
	v_mov_b32_e32 v11, v2
	v_mov_b32_e32 v12, v2
	v_mov_b32_e32 v13, v2
	v_mov_b32_e32 v14, v2
	v_mov_b32_e32 v15, v2
	v_mov_b32_e32 v16, v2
	v_mov_b32_e32 v17, v2
	v_or_b32_e32 v139, v22, v20
	v_add3_u32 v142, v0, v18, 0
	s_mov_b64 s[2:3], -1
	s_waitcnt lgkmcnt(0)
	s_barrier

.LBB0_374:
	v_add_u32_e32 v137, s2, v141
	v_add_u32_e32 v250, s2, v142
	v_add_u32_e32 v250, 0x11000, v250
	ds_read_b128 v[184:187], v137 offset:0
	ds_read_b128 v[188:191], v137 offset:16
	ds_read_b128 v[192:195], v137 offset:32
	ds_read_b128 v[196:199], v137 offset:48
	ds_read_b128 v[200:203], v137 offset:64
	ds_read_b128 v[204:207], v137 offset:80
	ds_read_b128 v[208:211], v137 offset:96
	ds_read_b128 v[212:215], v137 offset:112
	s_waitcnt lgkmcnt(7)
	v_mfma_f32_32x32x16_bf16 v[82:97], v[184:187], v[98:101], v[2:17]
	s_waitcnt lgkmcnt(6)
	v_mfma_f32_32x32x16_bf16 v[82:97], v[188:191], v[102:105], v[82:97]
	s_waitcnt lgkmcnt(5)
	v_mfma_f32_32x32x16_bf16 v[82:97], v[192:195], v[106:109], v[82:97]
	s_waitcnt lgkmcnt(4)
	v_mfma_f32_32x32x16_bf16 v[82:97], v[196:199], v[110:113], v[82:97]
	s_waitcnt lgkmcnt(3)
	v_mfma_f32_32x32x16_bf16 v[82:97], v[200:203], v[114:117], v[82:97]
	s_waitcnt lgkmcnt(2)
	v_mfma_f32_32x32x16_bf16 v[82:97], v[204:207], v[118:121], v[82:97]
	s_waitcnt lgkmcnt(1)
	v_mfma_f32_32x32x16_bf16 v[82:97], v[208:211], v[122:125], v[82:97]
	s_waitcnt lgkmcnt(0)
	v_mfma_f32_32x32x16_bf16 v[82:97], v[212:215], v[126:129], v[82:97]
	ds_read_b64_tr_b16 v[184:185], v250 offset:0
	ds_read_b64_tr_b16 v[186:187], v250 offset:2176
	ds_read_b64_tr_b16 v[188:189], v250 offset:4352
	ds_read_b64_tr_b16 v[190:191], v250 offset:6528
	ds_read_b64_tr_b16 v[192:193], v250 offset:64
	ds_read_b64_tr_b16 v[194:195], v250 offset:2240
	ds_read_b64_tr_b16 v[196:197], v250 offset:4416
	ds_read_b64_tr_b16 v[198:199], v250 offset:6592
	s_nop 3
	v_exp_f32_e32 v216, v82
	v_exp_f32_e32 v217, v83
	v_exp_f32_e32 v218, v84
	v_add_f32_e32 v0, v0, v216
	v_exp_f32_e32 v219, v85
	v_add_f32_e32 v0, v217, v0
	v_exp_f32_e32 v220, v86
	v_add_f32_e32 v0, v218, v0
	v_exp_f32_e32 v221, v87
	v_add_f32_e32 v0, v219, v0
	v_exp_f32_e32 v222, v88
	v_add_f32_e32 v0, v220, v0
	v_exp_f32_e32 v223, v89
	v_add_f32_e32 v0, v221, v0
	v_exp_f32_e32 v90, v90
	v_add_f32_e32 v0, v222, v0
	v_exp_f32_e32 v91, v91
	v_add_f32_e32 v0, v223, v0
	v_exp_f32_e32 v92, v92
	v_add_f32_e32 v0, v90, v0
	v_exp_f32_e32 v93, v93
	v_add_f32_e32 v0, v91, v0
	v_exp_f32_e32 v94, v94
	v_add_f32_e32 v0, v92, v0
	v_exp_f32_e32 v95, v95
	v_add_f32_e32 v0, v93, v0
	v_exp_f32_e32 v96, v96
	v_add_f32_e32 v0, v94, v0
	v_exp_f32_e32 v97, v97
	v_add_f32_e32 v0, v95, v0
	v_add_f32_e32 v0, v96, v0
	v_add_f32_e32 v0, v97, v0
	v_cvt_pk_bf16_f32 v82, v216, v217
	v_cvt_pk_bf16_f32 v83, v218, v219
	v_cvt_pk_bf16_f32 v84, v220, v221
	v_cvt_pk_bf16_f32 v85, v222, v223
	v_cvt_pk_bf16_f32 v86, v90, v91
	v_cvt_pk_bf16_f32 v87, v92, v93
	v_cvt_pk_bf16_f32 v88, v94, v95
	v_cvt_pk_bf16_f32 v89, v96, v97
	s_waitcnt lgkmcnt(0)
	ds_read_b64_tr_b16 v[200:201], v250 offset:128
	ds_read_b64_tr_b16 v[202:203], v250 offset:2304
	ds_read_b64_tr_b16 v[204:205], v250 offset:4480
	ds_read_b64_tr_b16 v[206:207], v250 offset:6656
	ds_read_b64_tr_b16 v[208:209], v250 offset:192
	ds_read_b64_tr_b16 v[210:211], v250 offset:2368
	ds_read_b64_tr_b16 v[212:213], v250 offset:4544
	ds_read_b64_tr_b16 v[214:215], v250 offset:6720
	v_mfma_f32_32x32x16_bf16 v[66:81], v[184:187], v[82:85], v[66:81]
	v_mfma_f32_32x32x16_bf16 v[66:81], v[188:191], v[86:89], v[66:81]
	v_mfma_f32_32x32x16_bf16 v[50:65], v[192:195], v[82:85], v[50:65]
	v_mfma_f32_32x32x16_bf16 v[50:65], v[196:199], v[86:89], v[50:65]
	s_waitcnt lgkmcnt(6)
	v_mfma_f32_32x32x16_bf16 v[34:49], v[200:203], v[82:85], v[34:49]
	s_waitcnt lgkmcnt(4)
	v_mfma_f32_32x32x16_bf16 v[34:49], v[204:207], v[86:89], v[34:49]
	s_waitcnt lgkmcnt(2)
	v_mfma_f32_32x32x16_bf16 v[18:33], v[208:211], v[82:85], v[18:33]
	s_waitcnt lgkmcnt(0)
	v_mfma_f32_32x32x16_bf16 v[18:33], v[212:215], v[86:89], v[18:33]
	ds_read_b128 v[184:187], v137 offset:8704
	ds_read_b128 v[188:191], v137 offset:8720
	ds_read_b128 v[192:195], v137 offset:8736
	ds_read_b128 v[196:199], v137 offset:8752
	ds_read_b128 v[200:203], v137 offset:8768
	ds_read_b128 v[204:207], v137 offset:8784
	ds_read_b128 v[208:211], v137 offset:8800
	ds_read_b128 v[212:215], v137 offset:8816
	s_waitcnt lgkmcnt(7)
	v_mfma_f32_32x32x16_bf16 v[82:97], v[184:187], v[98:101], v[2:17]
	s_waitcnt lgkmcnt(6)
	v_mfma_f32_32x32x16_bf16 v[82:97], v[188:191], v[102:105], v[82:97]
	s_waitcnt lgkmcnt(5)
	v_mfma_f32_32x32x16_bf16 v[82:97], v[192:195], v[106:109], v[82:97]
	s_waitcnt lgkmcnt(4)
	v_mfma_f32_32x32x16_bf16 v[82:97], v[196:199], v[110:113], v[82:97]
	s_waitcnt lgkmcnt(3)
	v_mfma_f32_32x32x16_bf16 v[82:97], v[200:203], v[114:117], v[82:97]
	s_waitcnt lgkmcnt(2)
	v_mfma_f32_32x32x16_bf16 v[82:97], v[204:207], v[118:121], v[82:97]
	s_waitcnt lgkmcnt(1)
	v_mfma_f32_32x32x16_bf16 v[82:97], v[208:211], v[122:125], v[82:97]
	s_waitcnt lgkmcnt(0)
	v_mfma_f32_32x32x16_bf16 v[82:97], v[212:215], v[126:129], v[82:97]
	ds_read_b64_tr_b16 v[184:185], v250 offset:8704
	ds_read_b64_tr_b16 v[186:187], v250 offset:10880
	ds_read_b64_tr_b16 v[188:189], v250 offset:13056
	ds_read_b64_tr_b16 v[190:191], v250 offset:15232
	ds_read_b64_tr_b16 v[192:193], v250 offset:8768
	ds_read_b64_tr_b16 v[194:195], v250 offset:10944
	ds_read_b64_tr_b16 v[196:197], v250 offset:13120
	ds_read_b64_tr_b16 v[198:199], v250 offset:15296
	s_nop 3
	v_exp_f32_e32 v216, v82
	v_exp_f32_e32 v217, v83
	v_exp_f32_e32 v218, v84
	v_add_f32_e32 v0, v0, v216
	v_exp_f32_e32 v219, v85
	v_add_f32_e32 v0, v217, v0
	v_exp_f32_e32 v220, v86
	v_add_f32_e32 v0, v218, v0
	v_exp_f32_e32 v221, v87
	v_add_f32_e32 v0, v219, v0
	v_exp_f32_e32 v222, v88
	v_add_f32_e32 v0, v220, v0
	v_exp_f32_e32 v223, v89
	v_add_f32_e32 v0, v221, v0
	v_exp_f32_e32 v90, v90
	v_add_f32_e32 v0, v222, v0
	v_exp_f32_e32 v91, v91
	v_add_f32_e32 v0, v223, v0
	v_exp_f32_e32 v92, v92
	v_add_f32_e32 v0, v90, v0
	v_exp_f32_e32 v93, v93
	v_add_f32_e32 v0, v91, v0
	v_exp_f32_e32 v94, v94
	v_add_f32_e32 v0, v92, v0
	v_exp_f32_e32 v95, v95
	v_add_f32_e32 v0, v93, v0
	v_exp_f32_e32 v96, v96
	v_add_f32_e32 v0, v94, v0
	v_exp_f32_e32 v97, v97
	v_add_f32_e32 v0, v95, v0
	v_add_f32_e32 v0, v96, v0
	v_add_f32_e32 v0, v97, v0
	v_cvt_pk_bf16_f32 v82, v216, v217
	v_cvt_pk_bf16_f32 v83, v218, v219
	v_cvt_pk_bf16_f32 v84, v220, v221
	v_cvt_pk_bf16_f32 v85, v222, v223
	v_cvt_pk_bf16_f32 v86, v90, v91
	v_cvt_pk_bf16_f32 v87, v92, v93
	v_cvt_pk_bf16_f32 v88, v94, v95
	v_cvt_pk_bf16_f32 v89, v96, v97
	s_waitcnt lgkmcnt(0)
	ds_read_b64_tr_b16 v[200:201], v250 offset:8832
	ds_read_b64_tr_b16 v[202:203], v250 offset:11008
	ds_read_b64_tr_b16 v[204:205], v250 offset:13184
	ds_read_b64_tr_b16 v[206:207], v250 offset:15360
	ds_read_b64_tr_b16 v[208:209], v250 offset:8896
	ds_read_b64_tr_b16 v[210:211], v250 offset:11072
	ds_read_b64_tr_b16 v[212:213], v250 offset:13248
	ds_read_b64_tr_b16 v[214:215], v250 offset:15424
	v_mfma_f32_32x32x16_bf16 v[66:81], v[184:187], v[82:85], v[66:81]
	v_mfma_f32_32x32x16_bf16 v[66:81], v[188:191], v[86:89], v[66:81]
	v_mfma_f32_32x32x16_bf16 v[50:65], v[192:195], v[82:85], v[50:65]
	v_mfma_f32_32x32x16_bf16 v[50:65], v[196:199], v[86:89], v[50:65]
	s_waitcnt lgkmcnt(6)
	v_mfma_f32_32x32x16_bf16 v[34:49], v[200:203], v[82:85], v[34:49]
	s_waitcnt lgkmcnt(4)
	v_mfma_f32_32x32x16_bf16 v[34:49], v[204:207], v[86:89], v[34:49]
	s_waitcnt lgkmcnt(2)
	v_mfma_f32_32x32x16_bf16 v[18:33], v[208:211], v[82:85], v[18:33]
	s_waitcnt lgkmcnt(0)
	v_mfma_f32_32x32x16_bf16 v[18:33], v[212:215], v[86:89], v[18:33]
	s_addk_i32 s2, 0x4400
	s_cmp_eq_u32 s2, 0x11000
	s_cbranch_scc0 .LBB0_374
	ds_bpermute_b32 v82, v138, v0
	v_ashrrev_i32_e32 v137, 31, v136
	s_mov_b32 s12, 32
	s_mov_b64 s[2:3], 0
	s_and_b64 vcc, exec, s[0:1]
	s_waitcnt lgkmcnt(0)
	v_add_f32_e32 v0, v0, v82
	v_rcp_f32_e32 v0, v0
	v_lshlrev_b64 v[82:83], 10, v[136:137]
	v_lshl_add_u64 v[82:83], v[132:133], 0, v[82:83]
	v_pk_mul_f32 v[66:67], v[66:67], v[0:1] op_sel_hi:[1,0]
	v_pk_mul_f32 v[68:69], v[68:69], v[0:1] op_sel_hi:[1,0]
	v_pk_mul_f32 v[50:51], v[50:51], v[0:1] op_sel_hi:[1,0]
	v_pk_mul_f32 v[52:53], v[52:53], v[0:1] op_sel_hi:[1,0]
	v_pk_mul_f32 v[34:35], v[34:35], v[0:1] op_sel_hi:[1,0]
	v_pk_mul_f32 v[36:37], v[36:37], v[0:1] op_sel_hi:[1,0]
	v_pk_mul_f32 v[18:19], v[18:19], v[0:1] op_sel_hi:[1,0]
	v_pk_mul_f32 v[20:21], v[20:21], v[0:1] op_sel_hi:[1,0]
	v_cvt_pk_bf16_f32 v66, v66, v67
	v_cvt_pk_bf16_f32 v67, v68, v69
	v_cvt_pk_bf16_f32 v50, v50, v51
	v_cvt_pk_bf16_f32 v51, v52, v53
	v_cvt_pk_bf16_f32 v34, v34, v35
	v_cvt_pk_bf16_f32 v35, v36, v37
	v_cvt_pk_bf16_f32 v18, v18, v19
	v_cvt_pk_bf16_f32 v19, v20, v21
	global_store_dwordx2 v[82:83], v[66:67], off
	v_pk_mul_f32 v[66:67], v[70:71], v[0:1] op_sel_hi:[1,0]
	v_pk_mul_f32 v[68:69], v[72:73], v[0:1] op_sel_hi:[1,0]
	global_store_dwordx2 v[82:83], v[50:51], off offset:64
	v_pk_mul_f32 v[50:51], v[54:55], v[0:1] op_sel_hi:[1,0]
	v_pk_mul_f32 v[52:53], v[56:57], v[0:1] op_sel_hi:[1,0]
	global_store_dwordx2 v[82:83], v[34:35], off offset:128
	v_pk_mul_f32 v[34:35], v[38:39], v[0:1] op_sel_hi:[1,0]
	v_pk_mul_f32 v[36:37], v[40:41], v[0:1] op_sel_hi:[1,0]
	global_store_dwordx2 v[82:83], v[18:19], off offset:192
	v_pk_mul_f32 v[18:19], v[22:23], v[0:1] op_sel_hi:[1,0]
	v_pk_mul_f32 v[20:21], v[24:25], v[0:1] op_sel_hi:[1,0]
	v_cvt_pk_bf16_f32 v66, v66, v67
	v_cvt_pk_bf16_f32 v67, v68, v69
	v_cvt_pk_bf16_f32 v50, v50, v51
	v_cvt_pk_bf16_f32 v51, v52, v53
	v_cvt_pk_bf16_f32 v34, v34, v35
	v_cvt_pk_bf16_f32 v35, v36, v37
	v_cvt_pk_bf16_f32 v18, v18, v19
	v_cvt_pk_bf16_f32 v19, v20, v21
	global_store_dwordx2 v[82:83], v[66:67], off offset:16
	v_pk_mul_f32 v[66:67], v[74:75], v[0:1] op_sel_hi:[1,0]
	v_pk_mul_f32 v[68:69], v[76:77], v[0:1] op_sel_hi:[1,0]
	global_store_dwordx2 v[82:83], v[50:51], off offset:80
	v_pk_mul_f32 v[50:51], v[58:59], v[0:1] op_sel_hi:[1,0]
	v_pk_mul_f32 v[52:53], v[60:61], v[0:1] op_sel_hi:[1,0]
	global_store_dwordx2 v[82:83], v[34:35], off offset:144
	v_pk_mul_f32 v[34:35], v[42:43], v[0:1] op_sel_hi:[1,0]
	v_pk_mul_f32 v[36:37], v[44:45], v[0:1] op_sel_hi:[1,0]
	global_store_dwordx2 v[82:83], v[18:19], off offset:208
	v_pk_mul_f32 v[18:19], v[26:27], v[0:1] op_sel_hi:[1,0]
	v_pk_mul_f32 v[20:21], v[28:29], v[0:1] op_sel_hi:[1,0]
	v_cvt_pk_bf16_f32 v66, v66, v67
	v_cvt_pk_bf16_f32 v67, v68, v69
	v_cvt_pk_bf16_f32 v50, v50, v51
	v_cvt_pk_bf16_f32 v51, v52, v53
	v_cvt_pk_bf16_f32 v34, v34, v35
	v_cvt_pk_bf16_f32 v35, v36, v37
	v_cvt_pk_bf16_f32 v18, v18, v19
	v_cvt_pk_bf16_f32 v19, v20, v21
	global_store_dwordx2 v[82:83], v[66:67], off offset:32
	v_pk_mul_f32 v[66:67], v[78:79], v[0:1] op_sel_hi:[1,0]
	v_pk_mul_f32 v[68:69], v[80:81], v[0:1] op_sel_hi:[1,0]
	global_store_dwordx2 v[82:83], v[50:51], off offset:96
	v_pk_mul_f32 v[50:51], v[62:63], v[0:1] op_sel_hi:[1,0]
	v_pk_mul_f32 v[52:53], v[64:65], v[0:1] op_sel_hi:[1,0]
	global_store_dwordx2 v[82:83], v[34:35], off offset:160
	v_pk_mul_f32 v[34:35], v[46:47], v[0:1] op_sel_hi:[1,0]
	v_pk_mul_f32 v[36:37], v[48:49], v[0:1] op_sel_hi:[1,0]
	global_store_dwordx2 v[82:83], v[18:19], off offset:224
	v_pk_mul_f32 v[18:19], v[30:31], v[0:1] op_sel_hi:[1,0]
	v_pk_mul_f32 v[20:21], v[32:33], v[0:1] op_sel_hi:[1,0]
	v_cvt_pk_bf16_f32 v66, v66, v67
	v_cvt_pk_bf16_f32 v67, v68, v69
	v_cvt_pk_bf16_f32 v50, v50, v51
	v_cvt_pk_bf16_f32 v51, v52, v53
	v_cvt_pk_bf16_f32 v34, v34, v35
	v_cvt_pk_bf16_f32 v35, v36, v37
	v_cvt_pk_bf16_f32 v18, v18, v19
	v_cvt_pk_bf16_f32 v19, v20, v21
	global_store_dwordx2 v[82:83], v[66:67], off offset:48
	global_store_dwordx2 v[82:83], v[50:51], off offset:112
	global_store_dwordx2 v[82:83], v[34:35], off offset:176
	global_store_dwordx2 v[82:83], v[18:19], off offset:240
	s_cbranch_vccz .LBB0_373
	s_add_i32 s48, s48, s92
	s_cmpk_gt_i32 s48, 0xff
	s_barrier
	s_cbranch_scc0 .LBB0_372

.LBB0_519:
	s_lshl_b32 s0, s28, 26
	s_add_u32 s0, s18, s0
	s_addc_u32 s1, s19, 0
	s_add_u32 s0, s0, 0x3c00000
	v_lshrrev_b32_e32 v17, 1, v13
	s_addc_u32 s1, s1, 0
	v_and_b32_e32 v17, 24, v17
	s_add_u32 s40, s18, 0x19c00000
	v_and_b32_e32 v16, 15, v13
	v_lshlrev_b32_e32 v18, 1, v17
	v_lshlrev_b32_e32 v13, 2, v13
	s_addc_u32 s41, s19, 0
	s_and_b32 s6, s20, 3
	v_lshl_or_b32 v179, s21, 6, v16
	v_lshl_or_b32 v16, v16, 6, v18
	s_lshl_b32 s7, s21, 13
	v_and_b32_e32 v13, 32, v13
	v_bitop3_b32 v18, v16, s7, v13 bitop3:0xde
	s_lshl_b32 s7, s6, 12
	s_add_i32 m0, s3, 0x18000
	v_lshl_add_u64 v[8:9], v[8:9], 0, s[24:25]
	v_bitop3_b32 v184, v16, s7, v13 bitop3:0xde
	s_waitcnt vmcnt(4)
	s_barrier
	global_load_lds_dwordx4 v[8:9], off
	v_lshl_add_u64 v[6:7], v[6:7], 0, s[24:25]
	s_add_i32 m0, s3, 0x1a000
	s_add_i32 s7, s3, 0x8000
	s_add_i32 s18, s3, 0xa000
	global_load_lds_dwordx4 v[6:7], off
	v_lshl_add_u64 v[4:5], v[4:5], 0, s[24:25]
	s_mov_b32 m0, s7
	s_add_u32 s20, s90, 0x20080
	global_load_lds_dwordx4 v[4:5], off
	v_lshl_add_u64 v[2:3], v[2:3], 0, s[24:25]
	s_mov_b32 m0, s18
	s_addc_u32 s21, s91, 0
	global_load_lds_dwordx4 v[2:3], off
	s_add_i32 m0, s3, 0x1c000
	v_lshl_add_u64 v[2:3], s[20:21], 0, v[162:163]
	global_load_lds_dwordx4 v[2:3], off
	v_lshl_add_u64 v[2:3], s[20:21], 0, v[164:165]
	s_add_i32 m0, s3, 0x1e000
	v_or_b32_e32 v186, 16, v179
	global_load_lds_dwordx4 v[2:3], off
	v_lshlrev_b32_e32 v2, 8, v179
	v_and_b32_e32 v185, 0xcf00, v2
	v_lshlrev_b32_e32 v2, 8, v186
	v_or_b32_e32 v188, 32, v179
	v_and_b32_e32 v187, 0xdf00, v2
	v_lshlrev_b32_e32 v2, 8, v188
	v_or_b32_e32 v190, 48, v179
	v_and_b32_e32 v189, 0xef00, v2
	v_lshlrev_b32_e32 v2, 8, v190
	v_add_u32_e32 v192, 0x80, v179
	v_and_b32_e32 v191, 0xff00, v2
	v_lshlrev_b32_e32 v2, 8, v192
	v_add_u32_e32 v194, 0x90, v179
	v_and_b32_e32 v193, 0xcf00, v2
	v_lshlrev_b32_e32 v2, 8, v194
	v_add_u32_e32 v196, 0xa0, v179
	v_and_b32_e32 v195, 0xdf00, v2
	v_lshlrev_b32_e32 v2, 8, v196
	v_add_u32_e32 v198, 0xb0, v179
	v_and_b32_e32 v197, 0xef00, v2
	v_lshlrev_b32_e32 v2, 8, v198
	v_and_b32_e32 v199, 0xff00, v2
	v_lshlrev_b32_e32 v2, 13, v0
	v_and_b32_e32 v2, 0xffffc000, v2
	v_lshl_add_u32 v2, v10, 10, v2
	v_and_b32_e32 v0, 1, v0
	v_lshl_or_b32 v0, v0, 6, v2
	v_lshl_add_u32 v166, v11, 1, v0
	v_lshlrev_b32_e32 v0, 13, v12
	v_and_b32_e32 v0, 0xffffc000, v0
	s_waitcnt vmcnt(6)
	v_lshl_add_u32 v0, v14, 10, v0
	v_and_b32_e32 v2, 1, v12
	v_lshl_or_b32 v0, v2, 6, v0
	s_ashr_i32 s19, s8, 31
	v_lshl_or_b32 v200, s6, 6, v17
	v_mov_b32_e32 v167, v1
	v_lshl_add_u32 v168, v15, 1, v0
	v_mov_b32_e32 v169, v1
	s_mov_b32 s20, 0
	v_add_u32_e32 v201, 0, v18
	s_barrier
	s_branch .LBB0_521
	s_nop 0
	s_nop 0
	s_nop 0
	s_nop 0
	s_nop 0
	s_nop 0
	s_nop 0
	s_nop 0
	s_nop 0
	s_nop 0
	s_nop 0
	s_nop 0
	s_nop 0
	s_nop 0
	s_nop 0
